# P2b rows also by slab; barrier P2->P2b slab-local as well (six slab-local barriers: P1->P2, P2->P2b, P6->P7, P7->P8, P8->P9, P9->P10)
# speedup vs baseline: 1.0186x; 1.0032x over previous
; __device__ __forceinline__ int opaque_tid() { int t = threadIdx.x; asm volatile("" : "+v"(t)); return t; }
; __device__ __forceinline__ void p2b_rows(const Params& P, int G) {
;     const int tid = opaque_tid(), lane = tid & 63, wave = tid >> 6;
;     const bf16_t* Z = (const bf16_t*)P.out; bf16_t* CQN = (bf16_t*)(P.ws + WS_CQN); bf16_t* CKVN = (bf16_t*)(P.ws + WS_CKVN);
;     const float* cs = (const float*)(P.ws + WS_CS); bf16_t* KR = (bf16_t*)(P.ws + WS_KROPE);
;     for (int m = blockIdx.x * 8 + wave; m < M; m += G * 8) {
;         const bf16_t* zr = Z + (size_t)m * ZC;
.Lgbar_end_2:
.LBB0_297:
	s_or_b64 exec, exec, s[0:1]
	v_mov_b32_e32 v1, v168
	s_waitcnt lgkmcnt(0)
	s_barrier
	s_and_b32 s1, s2, 7
	s_lshl_b32 s1, s1, 11
	s_lshr_b32 s0, s2, 3
	s_lshl_b32 s0, s0, 3
	s_add_i32 s0, s0, s1
	s_lshl_b32 s1, s2, 3
	s_cmpk_eq_u32 s92, 0x100
	s_cselect_b32 s0, s0, s1
	v_ashrrev_i32_e32 v0, 6, v1
	s_nop 0
	v_add_u32_e32 v0, s0, v0
	s_movk_i32 s0, 0x4000
	v_cmp_gt_i32_e32 vcc, s0, v0
	s_and_saveexec_b64 s[22:23], vcc
	s_cbranch_execz .LBB0_302
	v_and_b32_e32 v12, 63, v1
	v_mbcnt_hi_u32_b32 v1, -1, v208
	v_and_b32_e32 v4, 64, v1
	v_add_u32_e32 v4, 64, v4
	v_xor_b32_e32 v5, 1, v1
	v_cmp_lt_i32_e32 vcc, v5, v4
	v_lshlrev_b32_e32 v2, 3, v12
	v_cmp_gt_u32_e64 s[0:1], 32, v12
	v_cndmask_b32_e32 v5, v1, v5, vcc
	v_lshlrev_b32_e32 v19, 2, v5
	v_xor_b32_e32 v5, 2, v1
	v_cmp_lt_i32_e32 vcc, v5, v4
	v_mov_b32_e32 v3, 0
	s_cmpk_eq_u32 s92, 0x100
	s_cselect_b32 s42, 0x100, s42
	s_ashr_i32 s43, s42, 31
	v_cndmask_b32_e32 v5, v1, v5, vcc
	v_lshlrev_b32_e32 v20, 2, v5
	v_xor_b32_e32 v5, 4, v1
	v_cmp_lt_i32_e32 vcc, v5, v4
	s_mov_b64 s[36:37], 0x19800000
	s_mov_b64 s[38:39], 0x18800000
	v_cndmask_b32_e32 v5, v1, v5, vcc
	v_lshlrev_b32_e32 v21, 2, v5
	v_xor_b32_e32 v5, 8, v1
	v_cmp_lt_i32_e32 vcc, v5, v4
	s_mov_b32 s52, 0x3b800000
	s_lshl_b64 s[24:25], s[42:43], 8
	v_cndmask_b32_e32 v5, v1, v5, vcc
	v_lshlrev_b32_e32 v22, 2, v5
	v_xor_b32_e32 v5, 16, v1
	v_cmp_lt_i32_e32 vcc, v5, v4
	s_lshl_b64 s[26:27], s[42:43], 7
	v_mov_b32_e32 v13, v3
	v_cndmask_b32_e32 v5, v1, v5, vcc
	v_lshlrev_b32_e32 v23, 2, v5
	v_xor_b32_e32 v5, 32, v1
	v_cmp_lt_i32_e32 vcc, v5, v4
	v_lshlrev_b32_e32 v4, 1, v12
	v_lshlrev_b32_e32 v12, 4, v12
	v_cndmask_b32_e32 v1, v1, v5, vcc
	v_lshlrev_b32_e32 v24, 2, v1
	v_ashrrev_i32_e32 v1, 31, v0
	v_lshlrev_b64 v[10:11], 9, v[0:1]
	v_lshlrev_b64 v[14:15], 10, v[0:1]
	v_lshlrev_b64 v[6:7], 8, v[0:1]
	v_lshlrev_b64 v[8:9], 7, v[0:1]
	v_or_b32_e32 v10, v10, v2
	v_or_b32_e32 v14, v14, v12
	v_lshlrev_b64 v[16:17], 13, v[0:1]
	v_mov_b32_e32 v5, v3
	v_lshl_add_u64 v[6:7], v[6:7], 0, v[2:3]
	v_or_b32_e32 v8, v8, v4
	v_lshl_add_u64 v[10:11], v[10:11], 0, s[36:37]
	s_lshl_b64 s[36:37], s[42:43], 9
	v_lshl_add_u64 v[14:15], v[14:15], 0, s[38:39]
	s_lshl_b64 s[40:41], s[42:43], 10
	v_lshl_add_u64 v[16:17], s[56:57], 0, v[16:17]
	s_lshl_b64 s[44:45], s[42:43], 13
	s_mov_b64 s[50:51], 0
	s_mov_b32 s53, 0x3b000000
	v_mov_b32_e32 v18, 0x358637bd
	s_mov_b32 s3, 0x800000
	s_movk_i32 s33, 0x7fff
	s_branch .LBB0_300
.LBB0_299:
	s_or_b64 exec, exec, s[38:39]
	v_add_u32_e32 v0, s42, v0
	s_and_b32 s38, s2, 7
	s_lshl_b32 s38, s38, 11
	s_addk_i32 s38, 0x7ff
	s_cmpk_eq_u32 s92, 0x100
	s_cselect_b32 s38, s38, 0x3fff
	v_cmp_lt_i32_e32 vcc, s38, v0
	v_lshl_add_u64 v[6:7], v[6:7], 0, s[24:25]
	v_lshl_add_u64 v[8:9], v[8:9], 0, s[26:27]
	v_lshl_add_u64 v[10:11], v[10:11], 0, s[36:37]
	v_lshl_add_u64 v[14:15], v[14:15], 0, s[40:41]
	s_or_b64 s[50:51], vcc, s[50:51]
	v_lshl_add_u64 v[16:17], v[16:17], 0, s[44:45]
	s_andn2_b64 exec, exec, s[50:51]
	s_cbranch_execz .LBB0_302

; __device__ __forceinline__ void xcd_barrier(const XcdBarrier& b) {
;     asm volatile("s_waitcnt vmcnt(0)" ::: "memory");
;     __syncthreads();
;     if (threadIdx.x == 0) {
;         unsigned* bar = b.bar;
;         __builtin_amdgcn_s_waitcnt(0);
;         unsigned nloc = b.st[0], nx = b.st[1];
;         if (nloc == 0u) { xcd_barrier_complete(bar, b.x, nloc, nx); b.st[0] = nloc; b.st[1] = nx; }
.LBB0_302:
	s_lshl_b32 s42, s92, 3
	s_or_b64 exec, exec, s[22:23]
	s_waitcnt vmcnt(0)
	s_barrier
	s_mov_b64 s[0:1], exec
	v_readlane_b32 s22, v241, 0
	v_readlane_b32 s23, v241, 1
	s_and_b64 s[22:23], s[0:1], s[22:23]
	s_mov_b64 exec, s[22:23]
	s_cbranch_execz .LBB0_354
	s_add_i32 s3, 0, 0x20160
	v_mov_b32_e32 v0, s3
	s_waitcnt vmcnt(0) expcnt(0) lgkmcnt(0)
	ds_read_b32 v2, v0
	s_add_i32 s3, 0, 0x20164
	v_mov_b32_e32 v0, s3
	ds_read_b32 v0, v0
	s_waitcnt lgkmcnt(1)
	v_cmp_ne_u32_e32 vcc, 0, v2
	s_cbranch_vccnz .LBB0_318
	s_mov_b32 s3, 1
	v_mov_b32_e32 v16, 0
	s_branch .LBB0_306
